# loop-head fetch alignment: the five main K-loop heads aligned to 64 bytes (on the flip-free, DPP-converted kernel)
# baseline (speedup 1.0000x reference)
; __device__ __forceinline__ int lane_fresh() { int l; asm volatile("v_mbcnt_lo_u32_b32 %0, -1, 0\n\tv_mbcnt_hi_u32_b32 %0, -1, %0" : "=v"(l)); return l; }
; #define WAIT_V(n) asm volatile("s_waitcnt vmcnt(" #n ")" ::: "memory")
; #define WAIT_L(n) asm volatile("s_waitcnt lgkmcnt(" #n ")" ::: "memory")
; #define BAR __builtin_amdgcn_s_barrier()
; template <int PART  , bool SYNC_FIRST = true>
; __device__ __forceinline__ void kloop_t(const u16* __restrict__ A, int lda, const u16* __restrict__ Bt, int ldb, int K, Acc& acc, const int wv) {
;     ...
;   const int wid = wv, lane = lane_fresh(), ktid = wv * 64 + lane, wr = wid >> 2, wc = wid & 3, fr = lane & 15, fq = lane >> 4;
;   bf16x8 At[4][2], B0[2][2], B1[2][2];
;   const int nt = K / BK;
;   unsigned oA0, oA1, oB0, oB1;
;   { int r_, c_; stage_rc(ktid * 16, r_, c_); oA0 = (unsigned)(r_ * lda + c_) * 2u; oB0 = (unsigned)(r_ * ldb + c_) * 2u;
;     stage_rc(ktid * 16 + 8192, r_, c_); oA1 = (unsigned)(r_ * lda + c_) * 2u; oB1 = (unsigned)(r_ * ldb + c_) * 2u; }
;   if (PART != 2) {
;     if (SYNC_FIRST) { WAIT_V(0); WAIT_L(0); __syncthreads(); }
;     STAGE(SB(0, 0), Bt, ldb, 0, 0); STAGE(SA(0, 0), A, lda, 0, 0);
;     STAGE(SB(0, 1), Bt, ldb, HALF, 0); STAGE(SA(0, 1), A, lda, HALF, 0);
;   }
;   if (PART == 1) return;
;   if (wr == 1) BAR;
;   WAIT_V(4); BAR;
;   STAGE(SB(1, 0), Bt, ldb, 0, 1); STAGE(SA(1, 0), A, lda, 0, 1); STAGE(SB(1, 1), Bt, ldb, HALF, 1);
;   WAIT_V(6); BAR;
; #pragma unroll 1
.Lkw_b1_join:
	v_ashrrev_i32_e32 v0, 6, v0
	v_ashrrev_i32_e32 v2, 5, v2
	v_and_or_b32 v5, v5, s70, v4
	v_and_b32_e32 v3, 32, v3
	v_and_or_b32 v8, v8, s70, v4
	v_and_b32_e32 v7, 32, v7
	v_and_or_b32 v11, v11, s70, v4
	v_and_b32_e32 v10, 32, v10
	v_and_or_b32 v4, v13, s70, v4
	v_and_b32_e32 v1, 32, v1
	v_add_lshl_u32 v153, v0, s56, 10
	v_add_lshl_u32 v154, v2, s56, 10
	v_add_lshl_u32 v155, v0, s58, 10
	v_add_lshl_u32 v156, v2, s58, 10
	v_xad_u32 v3, v5, v3, 16
	v_add_lshl_u32 v5, v0, s59, 10
	v_add_lshl_u32 v6, v2, s59, 10
	v_xad_u32 v7, v8, v7, 16
	v_add_lshl_u32 v8, v0, s61, 10
	v_add_lshl_u32 v9, v2, s61, 10
	v_xad_u32 v10, v11, v10, 16
	v_add_lshl_u32 v11, v0, s63, 10
	v_add_lshl_u32 v12, v2, s63, 10
	v_xad_u32 v1, v4, v1, 16
	v_add_lshl_u32 v4, v0, s65, 10
	v_add_lshl_u32 v2, v2, s65, 10
	v_mov_b32_e32 v0, 0
	s_mov_b32 s39, -2
	s_mov_b64 s[40:41], 0
	v_add_u32_e32 v130, v3, v5
	v_add_u32_e32 v131, v3, v6
	v_add_u32_e32 v132, v7, v8
	v_add_u32_e32 v133, v7, v9
	v_add_u32_e32 v134, v10, v11
	v_add_u32_e32 v135, v10, v12
	v_add_u32_e32 v137, v1, v4
	v_add_u32_e32 v138, v1, v2
	v_mov_b32_e32 v1, v0
	v_mov_b32_e32 v2, v0
	v_mov_b32_e32 v3, v0
	v_mov_b32_e32 v4, v0
	v_mov_b32_e32 v5, v0
	v_mov_b32_e32 v6, v0
	v_mov_b32_e32 v7, v0
	v_mov_b32_e32 v8, v0
	v_mov_b32_e32 v9, v0
	v_mov_b32_e32 v10, v0
	v_mov_b32_e32 v11, v0
	v_mov_b32_e32 v12, v0
	v_mov_b32_e32 v13, v0
	v_mov_b32_e32 v14, v0
	v_mov_b32_e32 v15, v0
	v_mov_b32_e32 v16, v0
	v_mov_b32_e32 v17, v0
	v_mov_b32_e32 v18, v0
	v_mov_b32_e32 v19, v0
	v_mov_b32_e32 v20, v0
	v_mov_b32_e32 v21, v0
	v_mov_b32_e32 v22, v0
	v_mov_b32_e32 v23, v0
	v_mov_b32_e32 v24, v0
	v_mov_b32_e32 v25, v0
	v_mov_b32_e32 v26, v0
	v_mov_b32_e32 v27, v0
	v_mov_b32_e32 v28, v0
	v_mov_b32_e32 v29, v0
	v_mov_b32_e32 v30, v0
	v_mov_b32_e32 v31, v0
	v_mov_b32_e32 v32, v0
	v_mov_b32_e32 v33, v0
	v_mov_b32_e32 v34, v0
	v_mov_b32_e32 v35, v0
	v_mov_b32_e32 v36, v0
	v_mov_b32_e32 v37, v0
	v_mov_b32_e32 v38, v0
	v_mov_b32_e32 v39, v0
	v_mov_b32_e32 v40, v0
	v_mov_b32_e32 v41, v0
	v_mov_b32_e32 v42, v0
	v_mov_b32_e32 v43, v0
	v_mov_b32_e32 v44, v0
	v_mov_b32_e32 v45, v0
	v_mov_b32_e32 v46, v0
	v_mov_b32_e32 v47, v0
	v_mov_b32_e32 v48, v0
	v_mov_b32_e32 v49, v0
	v_mov_b32_e32 v50, v0
	v_mov_b32_e32 v51, v0
	v_mov_b32_e32 v52, v0
	v_mov_b32_e32 v53, v0
	v_mov_b32_e32 v54, v0
	v_mov_b32_e32 v55, v0
	v_mov_b32_e32 v56, v0
	v_mov_b32_e32 v57, v0
	v_mov_b32_e32 v58, v0
	v_mov_b32_e32 v59, v0
	v_mov_b32_e32 v60, v0
	v_mov_b32_e32 v61, v0
	v_mov_b32_e32 v62, v0
	v_mov_b32_e32 v63, v0
	v_mov_b32_e32 v64, v0
	v_mov_b32_e32 v65, v0
	v_mov_b32_e32 v66, v0
	v_mov_b32_e32 v67, v0
	v_mov_b32_e32 v68, v0
	v_mov_b32_e32 v69, v0
	v_mov_b32_e32 v70, v0
	v_mov_b32_e32 v71, v0
	v_mov_b32_e32 v72, v0
	v_mov_b32_e32 v73, v0
	v_mov_b32_e32 v74, v0
	v_mov_b32_e32 v75, v0
	v_mov_b32_e32 v76, v0
	v_mov_b32_e32 v77, v0
	v_mov_b32_e32 v78, v0
	v_mov_b32_e32 v79, v0
	v_mov_b32_e32 v80, v0
	v_mov_b32_e32 v81, v0
	v_mov_b32_e32 v82, v0
	v_mov_b32_e32 v83, v0
	v_mov_b32_e32 v84, v0
	v_mov_b32_e32 v85, v0
	v_mov_b32_e32 v86, v0
	v_mov_b32_e32 v87, v0
	v_mov_b32_e32 v88, v0
	v_mov_b32_e32 v89, v0
	v_mov_b32_e32 v90, v0
	v_mov_b32_e32 v91, v0
	v_mov_b32_e32 v92, v0
	v_mov_b32_e32 v93, v0
	v_mov_b32_e32 v94, v0
	v_mov_b32_e32 v95, v0
	v_mov_b32_e32 v96, v0
	v_mov_b32_e32 v97, v0
	v_mov_b32_e32 v98, v0
	v_mov_b32_e32 v99, v0
	v_mov_b32_e32 v100, v0
	v_mov_b32_e32 v101, v0
	v_mov_b32_e32 v102, v0
	v_mov_b32_e32 v103, v0
	v_mov_b32_e32 v104, v0
	v_mov_b32_e32 v105, v0
	v_mov_b32_e32 v106, v0
	v_mov_b32_e32 v107, v0
	v_mov_b32_e32 v108, v0
	v_mov_b32_e32 v109, v0
	v_mov_b32_e32 v110, v0
	v_mov_b32_e32 v111, v0
	v_mov_b32_e32 v112, v0
	v_mov_b32_e32 v113, v0
	v_mov_b32_e32 v114, v0
	v_mov_b32_e32 v115, v0
	v_mov_b32_e32 v116, v0
	v_mov_b32_e32 v117, v0
	v_mov_b32_e32 v118, v0
	v_mov_b32_e32 v119, v0
	v_mov_b32_e32 v120, v0
	v_mov_b32_e32 v121, v0
	v_mov_b32_e32 v122, v0
	v_mov_b32_e32 v123, v0
	v_mov_b32_e32 v124, v0
	v_mov_b32_e32 v125, v0
	v_mov_b32_e32 v126, v0
	v_mov_b32_e32 v127, v0
	s_barrier
	.p2align	6

; __device__ __forceinline__ int lane_fresh() { int l; asm volatile("v_mbcnt_lo_u32_b32 %0, -1, 0\n\tv_mbcnt_hi_u32_b32 %0, -1, %0" : "=v"(l)); return l; }
; #define WAIT_V(n) asm volatile("s_waitcnt vmcnt(" #n ")" ::: "memory")
; #define WAIT_L(n) asm volatile("s_waitcnt lgkmcnt(" #n ")" ::: "memory")
; #define BAR __builtin_amdgcn_s_barrier()
; template <int PART  , bool SYNC_FIRST = true>
; __device__ __forceinline__ void kloop_t(const u16* __restrict__ A, int lda, const u16* __restrict__ Bt, int ldb, int K, Acc& acc, const int wv) {
;     ...
;   const int wid = wv, lane = lane_fresh(), ktid = wv * 64 + lane, wr = wid >> 2, wc = wid & 3, fr = lane & 15, fq = lane >> 4;
;   bf16x8 At[4][2], B0[2][2], B1[2][2];
;   const int nt = K / BK;
;   unsigned oA0, oA1, oB0, oB1;
;   { int r_, c_; stage_rc(ktid * 16, r_, c_); oA0 = (unsigned)(r_ * lda + c_) * 2u; oB0 = (unsigned)(r_ * ldb + c_) * 2u;
;     stage_rc(ktid * 16 + 8192, r_, c_); oA1 = (unsigned)(r_ * lda + c_) * 2u; oB1 = (unsigned)(r_ * ldb + c_) * 2u; }
;   if (PART != 2) {
;     if (SYNC_FIRST) { WAIT_V(0); WAIT_L(0); __syncthreads(); }
;     STAGE(SB(0, 0), Bt, ldb, 0, 0); STAGE(SA(0, 0), A, lda, 0, 0);
;     STAGE(SB(0, 1), Bt, ldb, HALF, 0); STAGE(SA(0, 1), A, lda, HALF, 0);
;   }
;   if (PART == 1) return;
;   if (wr == 1) BAR;
;   WAIT_V(4); BAR;
;   STAGE(SB(1, 0), Bt, ldb, 0, 1); STAGE(SA(1, 0), A, lda, 0, 1); STAGE(SB(1, 1), Bt, ldb, HALF, 1);
;   WAIT_V(6); BAR;
.LBB0_703:
	v_lshl_add_u32 v131, v134, 4, s76
	v_ashrrev_i32_e32 v0, 31, v131
	v_lshrrev_b32_e32 v0, 22, v0
	v_add_u32_e32 v0, v131, v0
	v_ashrrev_i32_e32 v0, 10, v0
	v_mul_i32_i24_e32 v130, 0x400, v0
	v_sub_u32_e32 v130, v131, v130
	v_lshrrev_b32_e32 v132, 4, v130
	v_bitop3_b32 v130, v132, v130, 32 bitop3:0x6c
	v_ashrrev_i32_e32 v133, 31, v130
	v_lshrrev_b32_e32 v133, 26, v133
	v_lshlrev_b32_e32 v132, 3, v0
	v_add_u32_e32 v133, v130, v133
	v_and_b32_e32 v132, 0x7ffffff0, v132
	v_ashrrev_i32_e32 v135, 6, v133
	v_and_b32_e32 v133, 0xc0, v133
	v_add_u32_e32 v132, v135, v132
	v_sub_u32_e32 v130, v130, v133
	v_lshlrev_b32_e32 v0, 5, v0
	v_ashrrev_i16_sdwa v130, v187, sext(v130) dst_sel:DWORD dst_unused:UNUSED_PAD src0_sel:DWORD src1_sel:BYTE_0
	v_mul_lo_u32 v132, v132, s56
	v_bfe_i32 v130, v130, 0, 16
	v_and_or_b32 v0, v0, 32, v132
	v_add_lshl_u32 v130, v0, v130, 1
	v_add_u32_e32 v0, 0x2000, v131
	v_ashrrev_i32_e32 v132, 31, v0
	v_lshrrev_b32_e32 v132, 22, v132
	v_add_u32_e32 v132, v0, v132
	v_ashrrev_i32_e32 v132, 10, v132
	v_mul_i32_i24_e32 v133, 0x400, v132
	v_sub_u32_e32 v0, v0, v133
	v_lshrrev_b32_e32 v133, 4, v0
	v_bitop3_b32 v0, v133, v0, 32 bitop3:0x6c
	v_ashrrev_i32_e32 v135, 31, v0
	v_lshrrev_b32_e32 v135, 26, v135
	v_add_u32_e32 v135, v0, v135
	v_ashrrev_i32_e32 v136, 6, v135
	v_and_b32_e32 v135, 0xffc0, v135
	v_sub_u32_e32 v0, v0, v135
	v_lshlrev_b32_e32 v133, 3, v132
	v_lshrrev_b16_e32 v135, 7, v0
	v_and_b32_e32 v133, 0x7ffffff0, v133
	v_and_b32_e32 v135, 1, v135
	v_add_u32_e32 v133, v136, v133
	v_add_u16_e32 v0, v0, v135
	v_lshlrev_b32_e32 v132, 5, v132
	v_ashrrev_i16_sdwa v0, v187, sext(v0) dst_sel:DWORD dst_unused:UNUSED_PAD src0_sel:DWORD src1_sel:BYTE_0
	v_mul_lo_u32 v133, v133, s56
	v_bfe_i32 v0, v0, 0, 16
	v_and_or_b32 v132, v132, 32, v133
	v_add_lshl_u32 v132, v132, v0, 1
	v_mov_b32_e32 v0, v130
	v_mov_b32_e32 v136, v132
	v_add_u32_e32 v133, s96, v131
	s_waitcnt vmcnt(4)
	s_barrier
	v_readfirstlane_b32 s6, v133
	v_lshl_add_u64 v[138:139], s[4:5], 0, v[0:1]
	v_mov_b32_e32 v137, v1
	v_add_u32_e32 v142, 0x2000, v133
	v_lshl_add_u64 v[138:139], v[138:139], 0, s[20:21]
	s_mov_b32 m0, s6
	v_lshl_add_u64 v[136:137], s[4:5], 0, v[136:137]
	v_readfirstlane_b32 s6, v142
	global_load_lds_dwordx4 v[138:139], off
	v_lshl_add_u64 v[136:137], v[136:137], 0, s[20:21]
	s_mov_b32 m0, s6
	v_add_u32_e32 v143, 16, v131
	global_load_lds_dwordx4 v[136:137], off
	v_mov_b32_e32 v0, v130
	v_mov_b32_e32 v136, v132
	v_add_u32_e32 v144, 0x8000, v143
	v_add_u32_e32 v145, 0xa000, v143
	v_lshl_add_u64 v[138:139], s[0:1], 0, v[0:1]
	v_readfirstlane_b32 s6, v144
	v_lshl_add_u64 v[138:139], v[138:139], 0, s[20:21]
	s_mov_b32 m0, s6
	v_mov_b32_e32 v137, v1
	v_readfirstlane_b32 s6, v145
	s_lshl_b32 s18, s56, 7
	global_load_lds_dwordx4 v[138:139], off
	v_lshl_add_u64 v[136:137], s[0:1], 0, v[136:137]
	s_mov_b32 m0, s6
	s_lshl_b64 s[6:7], s[18:19], 1
	v_lshl_add_u64 v[136:137], v[136:137], 0, s[20:21]
	s_add_u32 s8, s4, s6
	global_load_lds_dwordx4 v[136:137], off
	s_addc_u32 s9, s5, s7
	v_mov_b32_e32 v0, v130
	v_mov_b32_e32 v136, v132
	v_add_u32_e32 v146, s97, v131
	v_mov_b32_e32 v137, v1
	v_lshl_add_u64 v[138:139], s[8:9], 0, v[0:1]
	v_readfirstlane_b32 s18, v146
	v_add_u32_e32 v147, 0x2000, v146
	v_lshl_add_u64 v[138:139], v[138:139], 0, s[20:21]
	s_mov_b32 m0, s18
	v_lshl_add_u64 v[136:137], s[8:9], 0, v[136:137]
	v_readfirstlane_b32 s18, v147
	global_load_lds_dwordx4 v[138:139], off
	v_lshl_add_u64 v[136:137], v[136:137], 0, s[20:21]
	s_mov_b32 m0, s18
	v_and_b32_e32 v0, 15, v134
	global_load_lds_dwordx4 v[136:137], off
	v_lshlrev_b32_e32 v138, 2, v134
	v_lshlrev_b32_e32 v136, 6, v0
	v_and_b32_e32 v137, 48, v134
	v_and_b32_e32 v138, 32, v138
	v_bitop3_b32 v136, v136, v138, v137 bitop3:0x36
	v_ashrrev_i32_e32 v135, 1, v134
	v_add_u32_e32 v148, s94, v136
	v_add_u32_e32 v149, s95, v136
	v_add_u32_e32 v150, s96, v136
	v_add_u32_e32 v151, s97, v136
	v_or_b32_e32 v136, s78, v0
	v_or_b32_e32 v140, s81, v0
	v_or_b32_e32 v157, s83, v0
	v_or_b32_e32 v0, s85, v0
	v_add_u32_e32 v135, 32, v135
	v_lshlrev_b32_e32 v138, 6, v136
	v_lshlrev_b32_e32 v136, 2, v136
	v_lshlrev_b32_e32 v141, 6, v140
	v_lshlrev_b32_e32 v140, 2, v140
	v_lshlrev_b32_e32 v158, 6, v157
	v_lshlrev_b32_e32 v157, 2, v157
	v_lshlrev_b32_e32 v160, 6, v0
	v_lshlrev_b32_e32 v0, 2, v0
	s_mov_b32 s57, s19
	s_waitcnt vmcnt(6)
	v_ashrrev_i32_e32 v134, 6, v134
	v_ashrrev_i32_e32 v135, 5, v135
	v_and_or_b32 v138, v138, s10, v137
	v_and_b32_e32 v136, 32, v136
	v_and_or_b32 v141, v141, s10, v137
	v_and_b32_e32 v140, 32, v140
	v_and_or_b32 v158, v158, s10, v137
	v_and_b32_e32 v157, 32, v157
	v_and_or_b32 v137, v160, s10, v137
	v_and_b32_e32 v0, 32, v0
	s_lshl_b64 s[56:57], s[56:57], 8
	v_xad_u32 v136, v138, v136, 16
	v_add_lshl_u32 v138, v134, s80, 10
	v_add_lshl_u32 v139, v135, s80, 10
	v_xad_u32 v140, v141, v140, 16
	v_add_lshl_u32 v141, v134, s82, 10
	v_add_lshl_u32 v156, v135, s82, 10
	v_xad_u32 v157, v158, v157, 16
	v_add_lshl_u32 v158, v134, s84, 10
	v_add_lshl_u32 v159, v135, s84, 10
	v_xad_u32 v0, v137, v0, 16
	v_add_lshl_u32 v160, v134, s86, 10
	v_add_lshl_u32 v161, v135, s86, 10
	s_add_u32 s18, s0, s56
	v_add_lshl_u32 v152, v134, s77, 10
	v_add_lshl_u32 v153, v135, s77, 10
	v_add_lshl_u32 v154, v134, s79, 10
	v_add_lshl_u32 v155, v135, s79, 10
	s_addc_u32 vcc_lo, s1, s57
	s_mov_b32 vcc_hi, -2
	s_mov_b64 s[56:57], 0
	v_add_u32_e32 v134, v136, v138
	v_add_u32_e32 v135, v136, v139
	v_add_u32_e32 v136, v140, v141
	v_add_u32_e32 v137, v140, v156
	v_add_u32_e32 v138, v157, v158
	v_add_u32_e32 v139, v157, v159
	v_add_u32_e32 v140, v0, v160
	v_add_u32_e32 v141, v0, v161
	s_barrier
	.p2align	6

; __device__ __forceinline__ int lane_fresh() { int l; asm volatile("v_mbcnt_lo_u32_b32 %0, -1, 0\n\tv_mbcnt_hi_u32_b32 %0, -1, %0" : "=v"(l)); return l; }
; #define WAIT_V(n) asm volatile("s_waitcnt vmcnt(" #n ")" ::: "memory")
; #define WAIT_L(n) asm volatile("s_waitcnt lgkmcnt(" #n ")" ::: "memory")
; #define BAR __builtin_amdgcn_s_barrier()
; template <int PART  , bool SYNC_FIRST = true>
; __device__ __forceinline__ void kloop_t(const u16* __restrict__ A, int lda, const u16* __restrict__ Bt, int ldb, int K, Acc& acc, const int wv) {
;     ...
;   const int wid = wv, lane = lane_fresh(), ktid = wv * 64 + lane, wr = wid >> 2, wc = wid & 3, fr = lane & 15, fq = lane >> 4;
;   bf16x8 At[4][2], B0[2][2], B1[2][2];
;   const int nt = K / BK;
;   unsigned oA0, oA1, oB0, oB1;
;   { int r_, c_; stage_rc(ktid * 16, r_, c_); oA0 = (unsigned)(r_ * lda + c_) * 2u; oB0 = (unsigned)(r_ * ldb + c_) * 2u;
;     stage_rc(ktid * 16 + 8192, r_, c_); oA1 = (unsigned)(r_ * lda + c_) * 2u; oB1 = (unsigned)(r_ * ldb + c_) * 2u; }
;   if (PART != 2) {
;     if (SYNC_FIRST) { WAIT_V(0); WAIT_L(0); __syncthreads(); }
;     STAGE(SB(0, 0), Bt, ldb, 0, 0); STAGE(SA(0, 0), A, lda, 0, 0);
;     STAGE(SB(0, 1), Bt, ldb, HALF, 0); STAGE(SA(0, 1), A, lda, HALF, 0);
;   }
;   if (PART == 1) return;
;   if (wr == 1) BAR;
;   WAIT_V(4); BAR;
;   STAGE(SB(1, 0), Bt, ldb, 0, 1); STAGE(SA(1, 0), A, lda, 0, 1); STAGE(SB(1, 1), Bt, ldb, HALF, 1);
;   WAIT_V(6); BAR;
; #pragma unroll 1
.LBB0_979:
	s_lshr_b32 s36, s70, 6
	s_and_b32 s36, s36, 3
	v_mov_b32_e32 v128, v130
	v_mov_b32_e32 v2, v131
	v_add_u32_e32 v149, s67, v1
	s_lshl_b32 s73, s36, 19
	s_waitcnt vmcnt(4)
	s_barrier
	v_readfirstlane_b32 s36, v149
	v_lshl_add_u64 v[4:5], s[34:35], 0, v[128:129]
	v_mov_b32_e32 v3, v129
	v_add_u32_e32 v150, 0x2000, v149
	v_lshl_add_u64 v[4:5], v[4:5], 0, s[12:13]
	s_mov_b32 m0, s36
	v_lshl_add_u64 v[2:3], s[34:35], 0, v[2:3]
	v_readfirstlane_b32 s36, v150
	global_load_lds_dwordx4 v[4:5], off
	v_lshl_add_u64 v[2:3], v[2:3], 0, s[12:13]
	s_mov_b32 m0, s36
	v_mov_b32_e32 v128, v130
	global_load_lds_dwordx4 v[2:3], off
	v_mov_b32_e32 v2, v131
	v_add_u32_e32 v151, 0x8000, v143
	s_lshl_b32 s37, s63, 11
	v_readfirstlane_b32 s36, v151
	v_lshl_add_u64 v[4:5], s[30:31], 0, v[128:129]
	v_mov_b32_e32 v3, v129
	v_add_u32_e32 v152, 0xa000, v143
	s_and_b32 s72, s37, 0x1f80000
	v_lshl_add_u64 v[4:5], v[4:5], 0, s[12:13]
	s_mov_b32 m0, s36
	v_lshl_add_u64 v[2:3], s[30:31], 0, v[2:3]
	v_readfirstlane_b32 s36, v152
	v_add_u32_e32 v153, s68, v1
	global_load_lds_dwordx4 v[4:5], off
	v_lshl_add_u64 v[2:3], v[2:3], 0, s[12:13]
	s_mov_b32 m0, s36
	s_add_u32 s34, s34, 0x40080
	v_readfirstlane_b32 s36, v153
	v_add_u32_e32 v154, 0x2000, v153
	global_load_lds_dwordx4 v[2:3], off
	s_addc_u32 s35, s35, 0
	v_mov_b32_e32 v2, v130
	v_mov_b32_e32 v3, v131
	s_mov_b32 m0, s36
	v_readfirstlane_b32 s36, v154
	v_and_b32_e32 v6, 15, v0
	global_load_lds_dwordx4 v2, s[34:35]
	s_mov_b32 m0, s36
	v_lshlrev_b32_e32 v4, 2, v0
	global_load_lds_dwordx4 v3, s[34:35]
	v_lshlrev_b32_e32 v2, 6, v6
	v_and_b32_e32 v3, 48, v0
	v_and_b32_e32 v4, 32, v4
	v_bitop3_b32 v2, v2, v4, v3 bitop3:0x36
	v_ashrrev_i32_e32 v1, 1, v0
	v_add_u32_e32 v155, s65, v2
	v_add_u32_e32 v156, s66, v2
	v_add_u32_e32 v157, s67, v2
	v_add_u32_e32 v158, s68, v2
	v_or_b32_e32 v2, s44, v6
	v_or_b32_e32 v7, s53, v6
	v_or_b32_e32 v10, s55, v6
	v_or_b32_e32 v6, s57, v6
	v_add_u32_e32 v1, 32, v1
	v_lshlrev_b32_e32 v4, 6, v2
	v_lshlrev_b32_e32 v2, 2, v2
	v_lshlrev_b32_e32 v8, 6, v7
	v_lshlrev_b32_e32 v7, 2, v7
	v_lshlrev_b32_e32 v11, 6, v10
	v_lshlrev_b32_e32 v10, 2, v10
	v_lshlrev_b32_e32 v13, 6, v6
	v_lshlrev_b32_e32 v6, 2, v6
	s_waitcnt vmcnt(6)
	v_ashrrev_i32_e32 v0, 6, v0
	v_ashrrev_i32_e32 v1, 5, v1
	v_and_or_b32 v4, v4, s69, v3
	v_and_b32_e32 v2, 32, v2
	v_and_or_b32 v8, v8, s69, v3
	v_and_b32_e32 v7, 32, v7
	v_and_or_b32 v11, v11, s69, v3
	v_and_b32_e32 v10, 32, v10
	v_and_or_b32 v3, v13, s69, v3
	v_and_b32_e32 v6, 32, v6
	v_add_lshl_u32 v159, v0, s43, 10
	v_add_lshl_u32 v160, v1, s43, 10
	v_add_lshl_u32 v161, v0, s45, 10
	v_add_lshl_u32 v162, v1, s45, 10
	v_xad_u32 v2, v4, v2, 16
	v_add_lshl_u32 v4, v0, s52, 10
	v_add_lshl_u32 v5, v1, s52, 10
	v_xad_u32 v7, v8, v7, 16
	v_add_lshl_u32 v8, v0, s54, 10
	v_add_lshl_u32 v9, v1, s54, 10
	v_xad_u32 v10, v11, v10, 16
	v_add_lshl_u32 v11, v0, s56, 10
	v_add_lshl_u32 v12, v1, s56, 10
	v_xad_u32 v3, v3, v6, 16
	v_add_lshl_u32 v6, v0, s58, 10
	v_add_lshl_u32 v1, v1, s58, 10
	v_mov_b32_e32 v0, 0
	s_mov_b32 s74, -2
	v_add_u32_e32 v132, v2, v4
	v_add_u32_e32 v133, v2, v5
	v_add_u32_e32 v135, v7, v8
	v_add_u32_e32 v136, v7, v9
	v_add_u32_e32 v137, v10, v11
	v_add_u32_e32 v138, v10, v12
	v_add_u32_e32 v139, v3, v6
	v_add_u32_e32 v140, v3, v1
	s_mov_b64 s[34:35], s[50:51]
	v_mov_b32_e32 v1, v0
	v_mov_b32_e32 v2, v0
	v_mov_b32_e32 v3, v0
	v_mov_b32_e32 v4, v0
	v_mov_b32_e32 v5, v0
	v_mov_b32_e32 v6, v0
	v_mov_b32_e32 v7, v0
	v_mov_b32_e32 v8, v0
	v_mov_b32_e32 v9, v0
	v_mov_b32_e32 v10, v0
	v_mov_b32_e32 v11, v0
	v_mov_b32_e32 v12, v0
	v_mov_b32_e32 v13, v0
	v_mov_b32_e32 v14, v0
	v_mov_b32_e32 v15, v0
	v_mov_b32_e32 v16, v0
	v_mov_b32_e32 v17, v0
	v_mov_b32_e32 v18, v0
	v_mov_b32_e32 v19, v0
	v_mov_b32_e32 v20, v0
	v_mov_b32_e32 v21, v0
	v_mov_b32_e32 v22, v0
	v_mov_b32_e32 v23, v0
	v_mov_b32_e32 v24, v0
	v_mov_b32_e32 v25, v0
	v_mov_b32_e32 v26, v0
	v_mov_b32_e32 v27, v0
	v_mov_b32_e32 v28, v0
	v_mov_b32_e32 v29, v0
	v_mov_b32_e32 v30, v0
	v_mov_b32_e32 v31, v0
	v_mov_b32_e32 v32, v0
	v_mov_b32_e32 v33, v0
	v_mov_b32_e32 v34, v0
	v_mov_b32_e32 v35, v0
	v_mov_b32_e32 v36, v0
	v_mov_b32_e32 v37, v0
	v_mov_b32_e32 v38, v0
	v_mov_b32_e32 v39, v0
	v_mov_b32_e32 v40, v0
	v_mov_b32_e32 v41, v0
	v_mov_b32_e32 v42, v0
	v_mov_b32_e32 v43, v0
	v_mov_b32_e32 v44, v0
	v_mov_b32_e32 v45, v0
	v_mov_b32_e32 v46, v0
	v_mov_b32_e32 v47, v0
	v_mov_b32_e32 v48, v0
	v_mov_b32_e32 v49, v0
	v_mov_b32_e32 v50, v0
	v_mov_b32_e32 v51, v0
	v_mov_b32_e32 v52, v0
	v_mov_b32_e32 v53, v0
	v_mov_b32_e32 v54, v0
	v_mov_b32_e32 v55, v0
	v_mov_b32_e32 v56, v0
	v_mov_b32_e32 v57, v0
	v_mov_b32_e32 v58, v0
	v_mov_b32_e32 v59, v0
	v_mov_b32_e32 v60, v0
	v_mov_b32_e32 v61, v0
	v_mov_b32_e32 v62, v0
	v_mov_b32_e32 v63, v0
	v_mov_b32_e32 v64, v0
	v_mov_b32_e32 v65, v0
	v_mov_b32_e32 v66, v0
	v_mov_b32_e32 v67, v0
	v_mov_b32_e32 v68, v0
	v_mov_b32_e32 v69, v0
	v_mov_b32_e32 v70, v0
	v_mov_b32_e32 v71, v0
	v_mov_b32_e32 v72, v0
	v_mov_b32_e32 v73, v0
	v_mov_b32_e32 v74, v0
	v_mov_b32_e32 v75, v0
	v_mov_b32_e32 v76, v0
	v_mov_b32_e32 v77, v0
	v_mov_b32_e32 v78, v0
	v_mov_b32_e32 v79, v0
	v_mov_b32_e32 v80, v0
	v_mov_b32_e32 v81, v0
	v_mov_b32_e32 v82, v0
	v_mov_b32_e32 v83, v0
	v_mov_b32_e32 v84, v0
	v_mov_b32_e32 v85, v0
	v_mov_b32_e32 v86, v0
	v_mov_b32_e32 v87, v0
	v_mov_b32_e32 v88, v0
	v_mov_b32_e32 v89, v0
	v_mov_b32_e32 v90, v0
	v_mov_b32_e32 v91, v0
	v_mov_b32_e32 v92, v0
	v_mov_b32_e32 v93, v0
	v_mov_b32_e32 v94, v0
	v_mov_b32_e32 v95, v0
	v_mov_b32_e32 v96, v0
	v_mov_b32_e32 v97, v0
	v_mov_b32_e32 v98, v0
	v_mov_b32_e32 v99, v0
	v_mov_b32_e32 v100, v0
	v_mov_b32_e32 v101, v0
	v_mov_b32_e32 v102, v0
	v_mov_b32_e32 v103, v0
	v_mov_b32_e32 v104, v0
	v_mov_b32_e32 v105, v0
	v_mov_b32_e32 v106, v0
	v_mov_b32_e32 v107, v0
	v_mov_b32_e32 v108, v0
	v_mov_b32_e32 v109, v0
	v_mov_b32_e32 v110, v0
	v_mov_b32_e32 v111, v0
	v_mov_b32_e32 v112, v0
	v_mov_b32_e32 v113, v0
	v_mov_b32_e32 v114, v0
	v_mov_b32_e32 v115, v0
	v_mov_b32_e32 v116, v0
	v_mov_b32_e32 v117, v0
	v_mov_b32_e32 v118, v0
	v_mov_b32_e32 v119, v0
	v_mov_b32_e32 v120, v0
	v_mov_b32_e32 v121, v0
	v_mov_b32_e32 v122, v0
	v_mov_b32_e32 v123, v0
	v_mov_b32_e32 v124, v0
	v_mov_b32_e32 v125, v0
	v_mov_b32_e32 v126, v0
	v_mov_b32_e32 v127, v0
	s_barrier
	.p2align	6

; __device__ __forceinline__ int lane_fresh() { int l; asm volatile("v_mbcnt_lo_u32_b32 %0, -1, 0\n\tv_mbcnt_hi_u32_b32 %0, -1, %0" : "=v"(l)); return l; }
; #define WAIT_V(n) asm volatile("s_waitcnt vmcnt(" #n ")" ::: "memory")
; #define WAIT_L(n) asm volatile("s_waitcnt lgkmcnt(" #n ")" ::: "memory")
; #define BAR __builtin_amdgcn_s_barrier()
; template <int PART  , bool SYNC_FIRST = true>
; __device__ __forceinline__ void kloop_t(const u16* __restrict__ A, int lda, const u16* __restrict__ Bt, int ldb, int K, Acc& acc, const int wv) {
;     ...
;   const int wid = wv, lane = lane_fresh(), ktid = wv * 64 + lane, wr = wid >> 2, wc = wid & 3, fr = lane & 15, fq = lane >> 4;
;   bf16x8 At[4][2], B0[2][2], B1[2][2];
;   const int nt = K / BK;
;   unsigned oA0, oA1, oB0, oB1;
;   { int r_, c_; stage_rc(ktid * 16, r_, c_); oA0 = (unsigned)(r_ * lda + c_) * 2u; oB0 = (unsigned)(r_ * ldb + c_) * 2u;
;     stage_rc(ktid * 16 + 8192, r_, c_); oA1 = (unsigned)(r_ * lda + c_) * 2u; oB1 = (unsigned)(r_ * ldb + c_) * 2u; }
;   if (PART != 2) {
;     if (SYNC_FIRST) { WAIT_V(0); WAIT_L(0); __syncthreads(); }
;     STAGE(SB(0, 0), Bt, ldb, 0, 0); STAGE(SA(0, 0), A, lda, 0, 0);
;     STAGE(SB(0, 1), Bt, ldb, HALF, 0); STAGE(SA(0, 1), A, lda, HALF, 0);
;   }
;   if (PART == 1) return;
;   if (wr == 1) BAR;
;   WAIT_V(4); BAR;
;   STAGE(SB(1, 0), Bt, ldb, 0, 1); STAGE(SA(1, 0), A, lda, 0, 1); STAGE(SB(1, 1), Bt, ldb, HALF, 1);
;   WAIT_V(6); BAR;
; #pragma unroll 1
.Lkw_f1_join:
	v_ashrrev_i32_e32 v0, 6, v0
	v_ashrrev_i32_e32 v2, 5, v2
	v_and_or_b32 v5, v5, s73, v4
	v_and_b32_e32 v3, 32, v3
	v_and_or_b32 v8, v8, s73, v4
	v_and_b32_e32 v7, 32, v7
	v_and_or_b32 v11, v11, s73, v4
	v_and_b32_e32 v10, 32, v10
	v_and_or_b32 v4, v13, s73, v4
	v_and_b32_e32 v1, 32, v1
	v_add_lshl_u32 v154, v0, s56, 10
	v_add_lshl_u32 v155, v2, s56, 10
	v_add_lshl_u32 v156, v0, s58, 10
	v_add_lshl_u32 v157, v2, s58, 10
	v_xad_u32 v3, v5, v3, 16
	v_add_lshl_u32 v5, v0, s59, 10
	v_add_lshl_u32 v6, v2, s59, 10
	v_xad_u32 v7, v8, v7, 16
	v_add_lshl_u32 v8, v0, s61, 10
	v_add_lshl_u32 v9, v2, s61, 10
	v_xad_u32 v10, v11, v10, 16
	v_add_lshl_u32 v11, v0, s63, 10
	v_add_lshl_u32 v12, v2, s63, 10
	v_xad_u32 v1, v4, v1, 16
	v_add_lshl_u32 v4, v0, s65, 10
	v_add_lshl_u32 v2, v2, s65, 10
	v_mov_b32_e32 v0, 0
	s_mov_b32 s81, -2
	v_add_u32_e32 v130, v3, v5
	v_add_u32_e32 v131, v3, v6
	v_add_u32_e32 v134, v7, v8
	v_add_u32_e32 v135, v7, v9
	v_add_u32_e32 v136, v10, v11
	v_add_u32_e32 v137, v10, v12
	v_add_u32_e32 v138, v1, v4
	v_add_u32_e32 v139, v1, v2
	s_mov_b64 s[38:39], s[50:51]
	v_mov_b32_e32 v1, v0
	v_mov_b32_e32 v2, v0
	v_mov_b32_e32 v3, v0
	v_mov_b32_e32 v4, v0
	v_mov_b32_e32 v5, v0
	v_mov_b32_e32 v6, v0
	v_mov_b32_e32 v7, v0
	v_mov_b32_e32 v8, v0
	v_mov_b32_e32 v9, v0
	v_mov_b32_e32 v10, v0
	v_mov_b32_e32 v11, v0
	v_mov_b32_e32 v12, v0
	v_mov_b32_e32 v13, v0
	v_mov_b32_e32 v14, v0
	v_mov_b32_e32 v15, v0
	v_mov_b32_e32 v16, v0
	v_mov_b32_e32 v17, v0
	v_mov_b32_e32 v18, v0
	v_mov_b32_e32 v19, v0
	v_mov_b32_e32 v20, v0
	v_mov_b32_e32 v21, v0
	v_mov_b32_e32 v22, v0
	v_mov_b32_e32 v23, v0
	v_mov_b32_e32 v24, v0
	v_mov_b32_e32 v25, v0
	v_mov_b32_e32 v26, v0
	v_mov_b32_e32 v27, v0
	v_mov_b32_e32 v28, v0
	v_mov_b32_e32 v29, v0
	v_mov_b32_e32 v30, v0
	v_mov_b32_e32 v31, v0
	v_mov_b32_e32 v32, v0
	v_mov_b32_e32 v33, v0
	v_mov_b32_e32 v34, v0
	v_mov_b32_e32 v35, v0
	v_mov_b32_e32 v36, v0
	v_mov_b32_e32 v37, v0
	v_mov_b32_e32 v38, v0
	v_mov_b32_e32 v39, v0
	v_mov_b32_e32 v40, v0
	v_mov_b32_e32 v41, v0
	v_mov_b32_e32 v42, v0
	v_mov_b32_e32 v43, v0
	v_mov_b32_e32 v44, v0
	v_mov_b32_e32 v45, v0
	v_mov_b32_e32 v46, v0
	v_mov_b32_e32 v47, v0
	v_mov_b32_e32 v48, v0
	v_mov_b32_e32 v49, v0
	v_mov_b32_e32 v50, v0
	v_mov_b32_e32 v51, v0
	v_mov_b32_e32 v52, v0
	v_mov_b32_e32 v53, v0
	v_mov_b32_e32 v54, v0
	v_mov_b32_e32 v55, v0
	v_mov_b32_e32 v56, v0
	v_mov_b32_e32 v57, v0
	v_mov_b32_e32 v58, v0
	v_mov_b32_e32 v59, v0
	v_mov_b32_e32 v60, v0
	v_mov_b32_e32 v61, v0
	v_mov_b32_e32 v62, v0
	v_mov_b32_e32 v63, v0
	v_mov_b32_e32 v64, v0
	v_mov_b32_e32 v65, v0
	v_mov_b32_e32 v66, v0
	v_mov_b32_e32 v67, v0
	v_mov_b32_e32 v68, v0
	v_mov_b32_e32 v69, v0
	v_mov_b32_e32 v70, v0
	v_mov_b32_e32 v71, v0
	v_mov_b32_e32 v72, v0
	v_mov_b32_e32 v73, v0
	v_mov_b32_e32 v74, v0
	v_mov_b32_e32 v75, v0
	v_mov_b32_e32 v76, v0
	v_mov_b32_e32 v77, v0
	v_mov_b32_e32 v78, v0
	v_mov_b32_e32 v79, v0
	v_mov_b32_e32 v80, v0
	v_mov_b32_e32 v81, v0
	v_mov_b32_e32 v82, v0
	v_mov_b32_e32 v83, v0
	v_mov_b32_e32 v84, v0
	v_mov_b32_e32 v85, v0
	v_mov_b32_e32 v86, v0
	v_mov_b32_e32 v87, v0
	v_mov_b32_e32 v88, v0
	v_mov_b32_e32 v89, v0
	v_mov_b32_e32 v90, v0
	v_mov_b32_e32 v91, v0
	v_mov_b32_e32 v92, v0
	v_mov_b32_e32 v93, v0
	v_mov_b32_e32 v94, v0
	v_mov_b32_e32 v95, v0
	v_mov_b32_e32 v96, v0
	v_mov_b32_e32 v97, v0
	v_mov_b32_e32 v98, v0
	v_mov_b32_e32 v99, v0
	v_mov_b32_e32 v100, v0
	v_mov_b32_e32 v101, v0
	v_mov_b32_e32 v102, v0
	v_mov_b32_e32 v103, v0
	v_mov_b32_e32 v104, v0
	v_mov_b32_e32 v105, v0
	v_mov_b32_e32 v106, v0
	v_mov_b32_e32 v107, v0
	v_mov_b32_e32 v108, v0
	v_mov_b32_e32 v109, v0
	v_mov_b32_e32 v110, v0
	v_mov_b32_e32 v111, v0
	v_mov_b32_e32 v112, v0
	v_mov_b32_e32 v113, v0
	v_mov_b32_e32 v114, v0
	v_mov_b32_e32 v115, v0
	v_mov_b32_e32 v116, v0
	v_mov_b32_e32 v117, v0
	v_mov_b32_e32 v118, v0
	v_mov_b32_e32 v119, v0
	v_mov_b32_e32 v120, v0
	v_mov_b32_e32 v121, v0
	v_mov_b32_e32 v122, v0
	v_mov_b32_e32 v123, v0
	v_mov_b32_e32 v124, v0
	v_mov_b32_e32 v125, v0
	v_mov_b32_e32 v126, v0
	v_mov_b32_e32 v127, v0
	s_barrier
	.p2align	6

; __device__ __forceinline__ int lane_fresh() { int l; asm volatile("v_mbcnt_lo_u32_b32 %0, -1, 0\n\tv_mbcnt_hi_u32_b32 %0, -1, %0" : "=v"(l)); return l; }
; #define WAIT_V(n) asm volatile("s_waitcnt vmcnt(" #n ")" ::: "memory")
; #define WAIT_L(n) asm volatile("s_waitcnt lgkmcnt(" #n ")" ::: "memory")
; #define BAR __builtin_amdgcn_s_barrier()
; template <int PART  , bool SYNC_FIRST = true>
; __device__ __forceinline__ void kloop_t(const u16* __restrict__ A, int lda, const u16* __restrict__ Bt, int ldb, int K, Acc& acc, const int wv) {
;     ...
;   const int wid = wv, lane = lane_fresh(), ktid = wv * 64 + lane, wr = wid >> 2, wc = wid & 3, fr = lane & 15, fq = lane >> 4;
;   bf16x8 At[4][2], B0[2][2], B1[2][2];
;   const int nt = K / BK;
;   unsigned oA0, oA1, oB0, oB1;
;   { int r_, c_; stage_rc(ktid * 16, r_, c_); oA0 = (unsigned)(r_ * lda + c_) * 2u; oB0 = (unsigned)(r_ * ldb + c_) * 2u;
;     stage_rc(ktid * 16 + 8192, r_, c_); oA1 = (unsigned)(r_ * lda + c_) * 2u; oB1 = (unsigned)(r_ * ldb + c_) * 2u; }
;   if (PART != 2) {
;     if (SYNC_FIRST) { WAIT_V(0); WAIT_L(0); __syncthreads(); }
;     STAGE(SB(0, 0), Bt, ldb, 0, 0); STAGE(SA(0, 0), A, lda, 0, 0);
;     STAGE(SB(0, 1), Bt, ldb, HALF, 0); STAGE(SA(0, 1), A, lda, HALF, 0);
;   }
;   if (PART == 1) return;
;   if (wr == 1) BAR;
;   WAIT_V(4); BAR;
;   STAGE(SB(1, 0), Bt, ldb, 0, 1); STAGE(SA(1, 0), A, lda, 0, 1); STAGE(SB(1, 1), Bt, ldb, HALF, 1);
;   WAIT_V(6); BAR;
; #pragma unroll 1
.LBB0_1138:
	s_lshr_b32 s44, s85, 6
	s_and_b32 s44, s44, 3
	s_lshl_b32 s55, s44, 21
	s_and_b32 s44, s84, 63
	v_mov_b32_e32 v2, v131
	v_mov_b32_e32 v128, v130
	v_add_u32_e32 v150, s80, v1
	s_lshl_b32 s56, s44, 21
	s_waitcnt vmcnt(4)
	s_barrier
	v_readfirstlane_b32 s44, v150
	v_lshl_add_u64 v[4:5], s[42:43], 0, v[128:129]
	v_mov_b32_e32 v3, v129
	v_add_u32_e32 v151, 0x2000, v150
	v_lshl_add_u64 v[4:5], v[4:5], 0, s[22:23]
	s_mov_b32 m0, s44
	v_lshl_add_u64 v[2:3], s[42:43], 0, v[2:3]
	v_readfirstlane_b32 s44, v151
	global_load_lds_dwordx4 v[4:5], off
	v_lshl_add_u64 v[2:3], v[2:3], 0, s[22:23]
	s_mov_b32 m0, s44
	v_mov_b32_e32 v128, v130
	global_load_lds_dwordx4 v[2:3], off
	v_mov_b32_e32 v2, v131
	v_add_u32_e32 v152, 0x8000, v144
	v_mov_b32_e32 v3, v129
	v_lshl_add_u64 v[4:5], s[4:5], 0, v[128:129]
	v_readfirstlane_b32 s44, v152
	v_add_u32_e32 v153, 0xa000, v144
	v_lshl_add_u64 v[4:5], v[4:5], 0, s[22:23]
	s_mov_b32 m0, s44
	v_lshl_add_u64 v[2:3], s[4:5], 0, v[2:3]
	v_readfirstlane_b32 s44, v153
	v_add_u32_e32 v154, s81, v1
	global_load_lds_dwordx4 v[4:5], off
	v_lshl_add_u64 v[2:3], v[2:3], 0, s[22:23]
	s_mov_b32 m0, s44
	s_add_u32 s42, s42, 0x100080
	v_readfirstlane_b32 s44, v154
	v_add_u32_e32 v155, 0x2000, v154
	global_load_lds_dwordx4 v[2:3], off
	s_addc_u32 s43, s43, 0
	v_mov_b32_e32 v2, v131
	v_mov_b32_e32 v3, v130
	s_mov_b32 m0, s44
	v_readfirstlane_b32 s44, v155
	v_and_b32_e32 v6, 15, v0
	global_load_lds_dwordx4 v3, s[42:43]
	s_mov_b32 m0, s44
	v_lshlrev_b32_e32 v4, 2, v0
	global_load_lds_dwordx4 v2, s[42:43]
	v_lshlrev_b32_e32 v2, 6, v6
	v_and_b32_e32 v3, 48, v0
	v_and_b32_e32 v4, 32, v4
	v_bitop3_b32 v2, v2, v4, v3 bitop3:0x36
	v_ashrrev_i32_e32 v1, 1, v0
	v_add_u32_e32 v156, s78, v2
	v_add_u32_e32 v157, s79, v2
	v_add_u32_e32 v158, s80, v2
	v_add_u32_e32 v159, s81, v2
	v_or_b32_e32 v2, s65, v6
	v_or_b32_e32 v7, s68, v6
	v_or_b32_e32 v10, s70, v6
	v_or_b32_e32 v6, s72, v6
	v_add_u32_e32 v1, 32, v1
	v_lshlrev_b32_e32 v4, 6, v2
	v_lshlrev_b32_e32 v2, 2, v2
	v_lshlrev_b32_e32 v8, 6, v7
	v_lshlrev_b32_e32 v7, 2, v7
	v_lshlrev_b32_e32 v11, 6, v10
	v_lshlrev_b32_e32 v10, 2, v10
	v_lshlrev_b32_e32 v13, 6, v6
	v_lshlrev_b32_e32 v6, 2, v6
	s_waitcnt vmcnt(6)
	v_ashrrev_i32_e32 v0, 6, v0
	v_ashrrev_i32_e32 v1, 5, v1
	v_and_or_b32 v4, v4, s82, v3
	v_and_b32_e32 v2, 32, v2
	v_and_or_b32 v8, v8, s82, v3
	v_and_b32_e32 v7, 32, v7
	v_and_or_b32 v11, v11, s82, v3
	v_and_b32_e32 v10, 32, v10
	v_and_or_b32 v3, v13, s82, v3
	v_and_b32_e32 v6, 32, v6
	v_add_lshl_u32 v160, v0, s64, 10
	v_add_lshl_u32 v161, v1, s64, 10
	v_add_lshl_u32 v162, v0, s66, 10
	v_add_lshl_u32 v163, v1, s66, 10
	v_xad_u32 v2, v4, v2, 16
	v_add_lshl_u32 v4, v0, s67, 10
	v_add_lshl_u32 v5, v1, s67, 10
	v_xad_u32 v7, v8, v7, 16
	v_add_lshl_u32 v8, v0, s69, 10
	v_add_lshl_u32 v9, v1, s69, 10
	v_xad_u32 v10, v11, v10, 16
	v_add_lshl_u32 v11, v0, s71, 10
	v_add_lshl_u32 v12, v1, s71, 10
	v_xad_u32 v3, v3, v6, 16
	v_add_lshl_u32 v6, v0, s73, 10
	v_add_lshl_u32 v1, v1, s73, 10
	v_mov_b32_e32 v0, 0
	s_mov_b32 s57, -2
	v_add_u32_e32 v132, v2, v4
	v_add_u32_e32 v133, v2, v5
	v_add_u32_e32 v134, v7, v8
	v_add_u32_e32 v135, v7, v9
	v_add_u32_e32 v136, v10, v11
	v_add_u32_e32 v137, v10, v12
	v_add_u32_e32 v138, v3, v6
	v_add_u32_e32 v139, v3, v1
	s_mov_b64 s[42:43], s[50:51]
	v_mov_b32_e32 v1, v0
	v_mov_b32_e32 v2, v0
	v_mov_b32_e32 v3, v0
	v_mov_b32_e32 v4, v0
	v_mov_b32_e32 v5, v0
	v_mov_b32_e32 v6, v0
	v_mov_b32_e32 v7, v0
	v_mov_b32_e32 v8, v0
	v_mov_b32_e32 v9, v0
	v_mov_b32_e32 v10, v0
	v_mov_b32_e32 v11, v0
	v_mov_b32_e32 v12, v0
	v_mov_b32_e32 v13, v0
	v_mov_b32_e32 v14, v0
	v_mov_b32_e32 v15, v0
	v_mov_b32_e32 v16, v0
	v_mov_b32_e32 v17, v0
	v_mov_b32_e32 v18, v0
	v_mov_b32_e32 v19, v0
	v_mov_b32_e32 v20, v0
	v_mov_b32_e32 v21, v0
	v_mov_b32_e32 v22, v0
	v_mov_b32_e32 v23, v0
	v_mov_b32_e32 v24, v0
	v_mov_b32_e32 v25, v0
	v_mov_b32_e32 v26, v0
	v_mov_b32_e32 v27, v0
	v_mov_b32_e32 v28, v0
	v_mov_b32_e32 v29, v0
	v_mov_b32_e32 v30, v0
	v_mov_b32_e32 v31, v0
	v_mov_b32_e32 v32, v0
	v_mov_b32_e32 v33, v0
	v_mov_b32_e32 v34, v0
	v_mov_b32_e32 v35, v0
	v_mov_b32_e32 v36, v0
	v_mov_b32_e32 v37, v0
	v_mov_b32_e32 v38, v0
	v_mov_b32_e32 v39, v0
	v_mov_b32_e32 v40, v0
	v_mov_b32_e32 v41, v0
	v_mov_b32_e32 v42, v0
	v_mov_b32_e32 v43, v0
	v_mov_b32_e32 v44, v0
	v_mov_b32_e32 v45, v0
	v_mov_b32_e32 v46, v0
	v_mov_b32_e32 v47, v0
	v_mov_b32_e32 v48, v0
	v_mov_b32_e32 v49, v0
	v_mov_b32_e32 v50, v0
	v_mov_b32_e32 v51, v0
	v_mov_b32_e32 v52, v0
	v_mov_b32_e32 v53, v0
	v_mov_b32_e32 v54, v0
	v_mov_b32_e32 v55, v0
	v_mov_b32_e32 v56, v0
	v_mov_b32_e32 v57, v0
	v_mov_b32_e32 v58, v0
	v_mov_b32_e32 v59, v0
	v_mov_b32_e32 v60, v0
	v_mov_b32_e32 v61, v0
	v_mov_b32_e32 v62, v0
	v_mov_b32_e32 v63, v0
	v_mov_b32_e32 v64, v0
	v_mov_b32_e32 v65, v0
	v_mov_b32_e32 v66, v0
	v_mov_b32_e32 v67, v0
	v_mov_b32_e32 v68, v0
	v_mov_b32_e32 v69, v0
	v_mov_b32_e32 v70, v0
	v_mov_b32_e32 v71, v0
	v_mov_b32_e32 v72, v0
	v_mov_b32_e32 v73, v0
	v_mov_b32_e32 v74, v0
	v_mov_b32_e32 v75, v0
	v_mov_b32_e32 v76, v0
	v_mov_b32_e32 v77, v0
	v_mov_b32_e32 v78, v0
	v_mov_b32_e32 v79, v0
	v_mov_b32_e32 v80, v0
	v_mov_b32_e32 v81, v0
	v_mov_b32_e32 v82, v0
	v_mov_b32_e32 v83, v0
	v_mov_b32_e32 v84, v0
	v_mov_b32_e32 v85, v0
	v_mov_b32_e32 v86, v0
	v_mov_b32_e32 v87, v0
	v_mov_b32_e32 v88, v0
	v_mov_b32_e32 v89, v0
	v_mov_b32_e32 v90, v0
	v_mov_b32_e32 v91, v0
	v_mov_b32_e32 v92, v0
	v_mov_b32_e32 v93, v0
	v_mov_b32_e32 v94, v0
	v_mov_b32_e32 v95, v0
	v_mov_b32_e32 v96, v0
	v_mov_b32_e32 v97, v0
	v_mov_b32_e32 v98, v0
	v_mov_b32_e32 v99, v0
	v_mov_b32_e32 v100, v0
	v_mov_b32_e32 v101, v0
	v_mov_b32_e32 v102, v0
	v_mov_b32_e32 v103, v0
	v_mov_b32_e32 v104, v0
	v_mov_b32_e32 v105, v0
	v_mov_b32_e32 v106, v0
	v_mov_b32_e32 v107, v0
	v_mov_b32_e32 v108, v0
	v_mov_b32_e32 v109, v0
	v_mov_b32_e32 v110, v0
	v_mov_b32_e32 v111, v0
	v_mov_b32_e32 v112, v0
	v_mov_b32_e32 v113, v0
	v_mov_b32_e32 v114, v0
	v_mov_b32_e32 v115, v0
	v_mov_b32_e32 v116, v0
	v_mov_b32_e32 v117, v0
	v_mov_b32_e32 v118, v0
	v_mov_b32_e32 v119, v0
	v_mov_b32_e32 v120, v0
	v_mov_b32_e32 v121, v0
	v_mov_b32_e32 v122, v0
	v_mov_b32_e32 v123, v0
	v_mov_b32_e32 v124, v0
	v_mov_b32_e32 v125, v0
	v_mov_b32_e32 v126, v0
	v_mov_b32_e32 v127, v0
	s_barrier
	.p2align	6
